# early L2 writeback by the 1/2 and 3/4 arrivers of each XCD
# baseline (speedup 1.0000x reference)
.LBB0_406:
	s_or_b64 exec, exec, s[4:5]
	v_cvt_f32_u32_e32 v5, v3
	s_waitcnt vmcnt(0)
	v_readfirstlane_b32 s2, v4
	v_sub_u32_e32 v4, 0, v3
	v_rcp_iflag_f32_e32 v5, v5
	v_add_u32_e32 v6, s2, v0
	v_mul_f32_e32 v5, 0x4f7ffffe, v5
	v_cvt_u32_f32_e32 v5, v5
	v_mul_lo_u32 v0, v4, v5
	v_mul_hi_u32 v0, v5, v0
	v_add_u32_e32 v0, v5, v0
	v_mul_hi_u32 v0, v6, v0
	v_mul_lo_u32 v4, v0, v3
	v_sub_u32_e32 v4, v6, v4
	v_add_u32_e32 v5, 1, v0
	v_cmp_ge_u32_e32 vcc, v4, v3
	s_nop 1
	v_cndmask_b32_e32 v0, v0, v5, vcc
	v_sub_u32_e32 v5, v4, v3
	v_cndmask_b32_e32 v4, v4, v5, vcc
	v_add_u32_e32 v5, 1, v0
	v_cmp_ge_u32_e32 vcc, v4, v3
	v_add_u32_e32 v4, 1, v6
	s_nop 0
	v_cndmask_b32_e32 v0, v0, v5, vcc
	v_mul_lo_u32 v5, v3, v0
	v_add_u32_e32 v3, v5, v3
	v_cmp_ne_u32_e32 vcc, v4, v3
	s_and_saveexec_b64 s[2:3], vcc
	s_xor_b64 s[2:3], exec, s[2:3]
	s_cbranch_execz .LBB0_420
	v_sub_u32_e32 v2, v6, v5
	v_sub_u32_e32 v4, v3, v5
	v_lshrrev_b32_e32 v7, 2, v4
	v_lshrrev_b32_e32 v4, 1, v4
	v_add_u32_e32 v7, v7, v4
	v_cmp_eq_u32_e32 vcc, v2, v4
	v_cmp_eq_u32_e64 s[4:5], v2, v7
	s_nop 1
	s_or_b64 vcc, vcc, s[4:5]
	s_cbranch_vccz .Learlywb_skip0
	buffer_wbl2 sc1

.LBB0_1268:
	s_or_b64 exec, exec, s[6:7]
	v_cvt_f32_u32_e32 v5, v3
	s_waitcnt vmcnt(0)
	v_readfirstlane_b32 s4, v4
	v_sub_u32_e32 v4, 0, v3
	v_rcp_iflag_f32_e32 v5, v5
	v_add_u32_e32 v6, s4, v0
	v_mul_f32_e32 v5, 0x4f7ffffe, v5
	v_cvt_u32_f32_e32 v5, v5
	v_mul_lo_u32 v0, v4, v5
	v_mul_hi_u32 v0, v5, v0
	v_add_u32_e32 v0, v5, v0
	v_mul_hi_u32 v0, v6, v0
	v_mul_lo_u32 v4, v0, v3
	v_sub_u32_e32 v4, v6, v4
	v_add_u32_e32 v5, 1, v0
	v_cmp_ge_u32_e32 vcc, v4, v3
	s_nop 1
	v_cndmask_b32_e32 v0, v0, v5, vcc
	v_sub_u32_e32 v5, v4, v3
	v_cndmask_b32_e32 v4, v4, v5, vcc
	v_add_u32_e32 v5, 1, v0
	v_cmp_ge_u32_e32 vcc, v4, v3
	v_add_u32_e32 v4, 1, v6
	s_nop 0
	v_cndmask_b32_e32 v0, v0, v5, vcc
	v_mul_lo_u32 v5, v3, v0
	v_add_u32_e32 v3, v5, v3
	v_cmp_ne_u32_e32 vcc, v4, v3
	s_and_saveexec_b64 s[4:5], vcc
	s_xor_b64 s[4:5], exec, s[4:5]
	s_cbranch_execz .LBB0_1282
	v_sub_u32_e32 v2, v6, v5
	v_sub_u32_e32 v4, v3, v5
	v_lshrrev_b32_e32 v7, 2, v4
	v_lshrrev_b32_e32 v4, 1, v4
	v_add_u32_e32 v7, v7, v4
	v_cmp_eq_u32_e32 vcc, v2, v4
	v_cmp_eq_u32_e64 s[4:5], v2, v7
	s_nop 1
	s_or_b64 vcc, vcc, s[4:5]
	s_cbranch_vccz .Learlywb_skip7
	buffer_wbl2 sc1
